# norm phases: 6-hop ds_bpermute wave sum replaced by DPP (xor 1,2,4,8) and permlane16/32 swaps, same pairwise adds
# baseline (speedup 1.0000x reference)
; __device__ __forceinline__ u32x2 pack4(f32x4 v) { u32x2 w; w.x = cvt_pk_bf16(v[0], v[1]); w.y = cvt_pk_bf16(v[2], v[3]); return w; }
; __device__ __forceinline__ float wave_sum(float v) {
; #pragma unroll
;     for (int o = 1; o < 64; o <<= 1) v += __shfl_xor(v, o);
;     return v;
; __device__ __forceinline__ void norm_phase(const float* xlat, const float* xctx, const float* gvec, const float* mod, int sh_off, int sc_off, bf16_t* H, int nrows,
;                                            const float* part, const float* pgate, float* xctx_out, int row_lo) {
;     ...
;         f32x4 v[4]; float ss = 0.f;
; #pragma unroll
;         for (int j = 0; j < 4; ++j) v[j] = vn[j];
;         if (row + NGW < nrows) NORM_LOADX(vn, row + NGW);
;         const float* mp = mod + bb * 6144;
;         f32x4 gg[4], sc[4], sh[4];
; #pragma unroll
;         for (int j = 0; j < 4; ++j) { const int col = 4 * lane + 256 * j; gg[j] = *(const f32x4*)(gvec + col); sc[j] = *(const f32x4*)(mp + sc_off + col); sh[j] = *(const f32x4*)(mp + sh_off + col); }
;         if (part != nullptr && row >= NLAT) {
; #pragma unroll
;             for (int j = 0; j < 4; ++j) {
;                 const size_t o = (size_t)(row - NLAT) * DM + 4 * lane + 256 * j;
;                 const f32x4 ps = (*(const f32x4*)(part + o) + *(const f32x4*)(part + (size_t)NCTX * DM + o)) + (*(const f32x4*)(part + (size_t)2 * NCTX * DM + o) + *(const f32x4*)(part + (size_t)3 * NCTX * DM + o));
;                 v[j] = v[j] + *(const f32x4*)(pgate + 4 * lane + 256 * j) * ps;
;                 *(f32x4*)(xctx_out + o) = v[j];
;             }
;         }
; #pragma unroll
;         for (int j = 0; j < 4; ++j) ss += (v[j][0] * v[j][0] + v[j][1] * v[j][1]) + (v[j][2] * v[j][2] + v[j][3] * v[j][3]);
;         const float rstd = __builtin_amdgcn_rsqf(wave_sum(ss) * (1.f / DM) + EPSV);
; #pragma unroll
;         for (int j = 0; j < 4; ++j) {
;             const int col = 4 * lane + 256 * j;
;             const f32x4 y = (v[j] * rstd) * gg[j];
;             const f32x4 hv = y * (sc[j] + 1.f) + sh[j];
;             *(u32x2*)(H + (size_t)row * DM + col) = pack4(hv);
;         }
.LBB0_175:
	s_or_b64 exec, exec, s[0:1]
	v_pk_mul_f32 v[106:107], v[14:15], v[14:15]
	v_pk_mul_f32 v[108:109], v[12:13], v[12:13]
	v_pk_mul_f32 v[96:97], v[10:11], v[10:11]
	v_pk_mul_f32 v[104:105], v[8:9], v[8:9]
	v_pk_mov_b32 v[110:111], v[108:109], v[106:107] op_sel:[1,0]
	v_mov_b32_e32 v109, v107
	v_pk_add_f32 v[106:107], v[110:111], v[108:109]
	v_pk_mov_b32 v[108:109], v[104:105], v[96:97] op_sel:[1,0]
	v_mov_b32_e32 v105, v97
	v_pk_add_f32 v[96:97], v[108:109], v[104:105]
	v_pk_add_f32 v[106:107], v[106:107], v[106:107] op_sel_hi:[0,1]
	v_pk_add_f32 v[96:97], v[96:97], v[96:97] op_sel_hi:[0,1]
	v_mul_f32_e32 v96, v4, v4
	v_pk_fma_f32 v[104:105], v[4:5], v[4:5], v[96:97] op_sel_hi:[1,1,0]
	v_mul_f32_e32 v96, v6, v6
	v_pk_fma_f32 v[108:109], v[6:7], v[6:7], v[96:97] op_sel_hi:[1,1,0]
	v_mul_f32_e32 v104, v0, v0
	v_mul_f32_e32 v108, v1, v1
	v_mul_f32_e32 v106, v2, v2
	v_mul_f32_e32 v96, v3, v3
	v_pk_add_f32 v[104:105], v[104:105], v[108:109]
	v_pk_add_f32 v[96:97], v[106:107], v[96:97]
	s_waitcnt vmcnt(15)
	v_pk_add_f32 v[78:79], v[78:79], 1.0 op_sel_hi:[1,0]
	v_pk_add_f32 v[96:97], v[104:105], v[96:97]
	v_pk_add_f32 v[76:77], v[76:77], 1.0 op_sel_hi:[1,0]
	v_add_f32_e32 v87, v96, v97
	s_nop 1
	s_and_b64 s[0:1], exec, vcc
	s_or_b64 s[10:11], s[0:1], s[10:11]
	v_readlane_b32 s0, v255, 24
	v_readlane_b32 s1, v255, 25
	s_waitcnt lgkmcnt(0)
	v_add_f32_dpp v87, v87, v87 quad_perm:[1,0,3,2] row_mask:0xf bank_mask:0xf
	s_nop 1
	v_lshl_add_u64 v[94:95], v[94:95], 0, s[80:81]
	s_waitcnt lgkmcnt(0)
	v_add_f32_dpp v87, v87, v87 quad_perm:[2,3,0,1] row_mask:0xf bank_mask:0xf
	s_nop 1
	s_waitcnt lgkmcnt(0)
	v_add_f32_dpp v87, v87, v87 row_half_mirror row_mask:0xf bank_mask:0xf
	s_nop 1
	s_waitcnt lgkmcnt(0)
	v_add_f32_dpp v87, v87, v87 row_mirror row_mask:0xf bank_mask:0xf
	v_mov_b32_e32 v89, v87
	s_nop 1
	s_waitcnt lgkmcnt(0)
	v_permlane16_swap_b32_e32 v87, v89
	v_add_f32_e32 v87, v87, v89
	v_mov_b32_e32 v89, v87
	s_nop 1
	s_waitcnt lgkmcnt(0)
	v_permlane32_swap_b32_e32 v87, v89
	v_add_f32_e32 v87, v87, v89
	v_fmamk_f32 v87, v87, 0x3a800000, v193
	v_rsq_f32_e32 v96, v87
	s_nop 0
	v_pk_mul_f32 v[14:15], v[14:15], v[96:97] op_sel_hi:[1,0]
	v_pk_mul_f32 v[12:13], v[12:13], v[96:97] op_sel_hi:[1,0]
	s_waitcnt vmcnt(13)
	v_pk_mul_f32 v[14:15], v[70:71], v[14:15]
	v_pk_mul_f32 v[12:13], v[68:69], v[12:13]
	v_pk_mul_f32 v[8:9], v[8:9], v[96:97] op_sel_hi:[1,0]
	v_pk_fma_f32 v[14:15], v[78:79], v[14:15], v[66:67]
	v_pk_fma_f32 v[12:13], v[76:77], v[12:13], v[64:65]
	v_pk_mul_f32 v[10:11], v[10:11], v[96:97] op_sel_hi:[1,0]
	s_waitcnt vmcnt(12)
	v_pk_mul_f32 v[8:9], v[56:57], v[8:9]
	v_cvt_pk_bf16_f32 v12, v12, v13
	v_cvt_pk_bf16_f32 v13, v14, v15
	s_waitcnt vmcnt(5)
	v_pk_add_f32 v[14:15], v[72:73], 1.0 op_sel_hi:[1,0]
	global_store_dwordx2 v[84:85], v[12:13], off
	v_pk_mul_f32 v[10:11], v[58:59], v[10:11]
	v_pk_add_f32 v[12:13], v[74:75], 1.0 op_sel_hi:[1,0]
	v_pk_fma_f32 v[8:9], v[14:15], v[8:9], v[60:61]
	v_pk_fma_f32 v[10:11], v[12:13], v[10:11], v[62:63]
	v_cvt_pk_bf16_f32 v8, v8, v9
	v_pk_mul_f32 v[6:7], v[6:7], v[96:97] op_sel_hi:[1,0]
	v_cvt_pk_bf16_f32 v9, v10, v11
	v_pk_mul_f32 v[4:5], v[4:5], v[96:97] op_sel_hi:[1,0]
	global_store_dwordx2 v[84:85], v[8:9], off offset:512
	v_pk_mul_f32 v[4:5], v[48:49], v[4:5]
	v_pk_mul_f32 v[6:7], v[50:51], v[6:7]
	v_pk_add_f32 v[8:9], v[54:55], 1.0 op_sel_hi:[1,0]
	v_pk_add_f32 v[10:11], v[52:53], 1.0 op_sel_hi:[1,0]
	v_pk_fma_f32 v[6:7], v[8:9], v[6:7], v[46:47]
	v_pk_fma_f32 v[4:5], v[10:11], v[4:5], v[44:45]
	v_pk_mul_f32 v[0:1], v[0:1], v[96:97] op_sel_hi:[1,0]
	v_cvt_pk_bf16_f32 v4, v4, v5
	v_cvt_pk_bf16_f32 v5, v6, v7
	v_pk_mul_f32 v[2:3], v[2:3], v[96:97] op_sel_hi:[1,0]
	v_pk_mul_f32 v[0:1], v[36:37], v[0:1]
	v_pk_add_f32 v[6:7], v[40:41], 1.0 op_sel_hi:[1,0]
	global_store_dwordx2 v[84:85], v[4:5], off offset:1024
	v_pk_mul_f32 v[2:3], v[38:39], v[2:3]
	v_pk_add_f32 v[4:5], v[42:43], 1.0 op_sel_hi:[1,0]
	s_waitcnt vmcnt(7)
	v_pk_fma_f32 v[0:1], v[6:7], v[0:1], v[32:33]
	v_pk_fma_f32 v[2:3], v[4:5], v[2:3], v[34:35]
	v_cvt_pk_bf16_f32 v0, v0, v1
	s_nop 0
	v_cvt_pk_bf16_f32 v1, v2, v3
	global_store_dwordx2 v[84:85], v[0:1], off offset:1536
	s_waitcnt vmcnt(4)
	v_mov_b64_e32 v[12:13], v[16:17]
	v_mov_b64_e32 v[8:9], v[20:21]
	v_mov_b64_e32 v[4:5], v[24:25]
	v_mov_b64_e32 v[0:1], v[28:29]
	v_lshl_add_u64 v[84:85], v[84:85], 0, s[0:1]
	v_mov_b32_e32 v96, v103
	v_mov_b64_e32 v[14:15], v[18:19]
	v_mov_b64_e32 v[10:11], v[22:23]
	v_mov_b64_e32 v[6:7], v[26:27]
	v_mov_b64_e32 v[2:3], v[30:31]
	s_andn2_b64 exec, exec, s[10:11]
	s_cbranch_execz .LBB0_180

; __device__ __forceinline__ u32x2 pack4(f32x4 v) { u32x2 w; w.x = cvt_pk_bf16(v[0], v[1]); w.y = cvt_pk_bf16(v[2], v[3]); return w; }
; __device__ __forceinline__ float wave_sum(float v) {
; #pragma unroll
;     for (int o = 1; o < 64; o <<= 1) v += __shfl_xor(v, o);
;     return v;
; __device__ __forceinline__ void norm_phase(const float* xlat, const float* xctx, const float* gvec, const float* mod, int sh_off, int sc_off, bf16_t* H, int nrows,
;                                            const float* part, const float* pgate, float* xctx_out, int row_lo) {
;     ...
;         f32x4 v[4]; float ss = 0.f;
; #pragma unroll
;         for (int j = 0; j < 4; ++j) v[j] = vn[j];
;         if (row + NGW < nrows) NORM_LOADX(vn, row + NGW);
;         const float* mp = mod + bb * 6144;
;         f32x4 gg[4], sc[4], sh[4];
; #pragma unroll
;         for (int j = 0; j < 4; ++j) { const int col = 4 * lane + 256 * j; gg[j] = *(const f32x4*)(gvec + col); sc[j] = *(const f32x4*)(mp + sc_off + col); sh[j] = *(const f32x4*)(mp + sh_off + col); }
;         if (part != nullptr && row >= NLAT) {
; #pragma unroll
;             for (int j = 0; j < 4; ++j) {
;                 const size_t o = (size_t)(row - NLAT) * DM + 4 * lane + 256 * j;
;                 const f32x4 ps = (*(const f32x4*)(part + o) + *(const f32x4*)(part + (size_t)NCTX * DM + o)) + (*(const f32x4*)(part + (size_t)2 * NCTX * DM + o) + *(const f32x4*)(part + (size_t)3 * NCTX * DM + o));
;                 v[j] = v[j] + *(const f32x4*)(pgate + 4 * lane + 256 * j) * ps;
;                 *(f32x4*)(xctx_out + o) = v[j];
;             }
;         }
; #pragma unroll
;         for (int j = 0; j < 4; ++j) ss += (v[j][0] * v[j][0] + v[j][1] * v[j][1]) + (v[j][2] * v[j][2] + v[j][3] * v[j][3]);
;         const float rstd = __builtin_amdgcn_rsqf(wave_sum(ss) * (1.f / DM) + EPSV);
; #pragma unroll
;         for (int j = 0; j < 4; ++j) {
;             const int col = 4 * lane + 256 * j;
;             const f32x4 y = (v[j] * rstd) * gg[j];
;             const f32x4 hv = y * (sc[j] + 1.f) + sh[j];
;             *(u32x2*)(H + (size_t)row * DM + col) = pack4(hv);
;         }
.LBB0_1137:
	s_or_b64 exec, exec, s[0:1]
	v_pk_mul_f32 v[100:101], v[14:15], v[14:15]
	v_pk_mul_f32 v[102:103], v[12:13], v[12:13]
	v_pk_mul_f32 v[96:97], v[10:11], v[10:11]
	v_pk_mul_f32 v[98:99], v[8:9], v[8:9]
	v_pk_mov_b32 v[104:105], v[102:103], v[100:101] op_sel:[1,0]
	v_mov_b32_e32 v103, v101
	v_pk_add_f32 v[100:101], v[104:105], v[102:103]
	v_pk_mov_b32 v[102:103], v[98:99], v[96:97] op_sel:[1,0]
	v_mov_b32_e32 v99, v97
	v_pk_add_f32 v[96:97], v[102:103], v[98:99]
	v_pk_add_f32 v[100:101], v[100:101], v[100:101] op_sel_hi:[0,1]
	v_pk_add_f32 v[96:97], v[96:97], v[96:97] op_sel_hi:[0,1]
	v_mul_f32_e32 v96, v4, v4
	v_pk_fma_f32 v[98:99], v[4:5], v[4:5], v[96:97] op_sel_hi:[1,1,0]
	v_mul_f32_e32 v96, v6, v6
	v_pk_fma_f32 v[102:103], v[6:7], v[6:7], v[96:97] op_sel_hi:[1,1,0]
	v_mul_f32_e32 v98, v0, v0
	v_mul_f32_e32 v102, v1, v1
	v_mul_f32_e32 v100, v2, v2
	v_mul_f32_e32 v96, v3, v3
	v_pk_add_f32 v[98:99], v[98:99], v[102:103]
	v_pk_add_f32 v[96:97], v[100:101], v[96:97]
	s_waitcnt vmcnt(11)
	v_pk_add_f32 v[78:79], v[78:79], 1.0 op_sel_hi:[1,0]
	v_pk_add_f32 v[96:97], v[98:99], v[96:97]
	v_pk_add_f32 v[76:77], v[76:77], 1.0 op_sel_hi:[1,0]
	v_add_f32_e32 v85, v96, v97
	s_nop 1
	s_and_b64 s[0:1], exec, vcc
	s_or_b64 s[8:9], s[0:1], s[8:9]
	v_readlane_b32 s0, v255, 24
	v_readlane_b32 s1, v255, 25
	s_waitcnt lgkmcnt(0)
	v_add_f32_dpp v85, v85, v85 quad_perm:[1,0,3,2] row_mask:0xf bank_mask:0xf
	s_nop 1
	v_lshl_add_u64 v[94:95], v[94:95], 0, s[80:81]
	s_waitcnt lgkmcnt(0)
	v_add_f32_dpp v85, v85, v85 quad_perm:[2,3,0,1] row_mask:0xf bank_mask:0xf
	s_nop 1
	s_waitcnt lgkmcnt(0)
	v_add_f32_dpp v85, v85, v85 row_half_mirror row_mask:0xf bank_mask:0xf
	s_nop 1
	s_waitcnt lgkmcnt(0)
	v_add_f32_dpp v85, v85, v85 row_mirror row_mask:0xf bank_mask:0xf
	v_mov_b32_e32 v87, v85
	s_nop 1
	s_waitcnt lgkmcnt(0)
	v_permlane16_swap_b32_e32 v85, v87
	v_add_f32_e32 v85, v85, v87
	v_mov_b32_e32 v87, v85
	s_nop 1
	s_waitcnt lgkmcnt(0)
	v_permlane32_swap_b32_e32 v85, v87
	v_add_f32_e32 v85, v85, v87
	v_fmamk_f32 v85, v85, 0x3a800000, v193
	v_rsq_f32_e32 v96, v85
	s_nop 0
	v_pk_mul_f32 v[14:15], v[14:15], v[96:97] op_sel_hi:[1,0]
	v_pk_mul_f32 v[12:13], v[12:13], v[96:97] op_sel_hi:[1,0]
	s_waitcnt vmcnt(9)
	v_pk_mul_f32 v[14:15], v[74:75], v[14:15]
	v_pk_mul_f32 v[12:13], v[72:73], v[12:13]
	v_pk_mul_f32 v[8:9], v[8:9], v[96:97] op_sel_hi:[1,0]
	v_pk_fma_f32 v[14:15], v[78:79], v[14:15], v[70:71]
	v_pk_fma_f32 v[12:13], v[76:77], v[12:13], v[68:69]
	v_pk_mul_f32 v[10:11], v[10:11], v[96:97] op_sel_hi:[1,0]
	s_waitcnt vmcnt(8)
	v_pk_mul_f32 v[8:9], v[60:61], v[8:9]
	v_cvt_pk_bf16_f32 v12, v12, v13
	v_cvt_pk_bf16_f32 v13, v14, v15
	s_waitcnt vmcnt(7)
	v_pk_add_f32 v[14:15], v[64:65], 1.0 op_sel_hi:[1,0]
	global_store_dwordx2 v[82:83], v[12:13], off
	v_pk_mul_f32 v[10:11], v[62:63], v[10:11]
	v_pk_add_f32 v[12:13], v[66:67], 1.0 op_sel_hi:[1,0]
	s_waitcnt vmcnt(7)
	v_pk_fma_f32 v[8:9], v[14:15], v[8:9], v[56:57]
	v_pk_fma_f32 v[10:11], v[12:13], v[10:11], v[58:59]
	v_cvt_pk_bf16_f32 v8, v8, v9
	v_pk_mul_f32 v[6:7], v[6:7], v[96:97] op_sel_hi:[1,0]
	v_cvt_pk_bf16_f32 v9, v10, v11
	v_pk_mul_f32 v[4:5], v[4:5], v[96:97] op_sel_hi:[1,0]
	global_store_dwordx2 v[82:83], v[8:9], off offset:512
	s_waitcnt vmcnt(5)
	v_pk_mul_f32 v[4:5], v[52:53], v[4:5]
	v_pk_mul_f32 v[6:7], v[54:55], v[6:7]
	v_pk_add_f32 v[8:9], v[50:51], 1.0 op_sel_hi:[1,0]
	v_pk_add_f32 v[10:11], v[48:49], 1.0 op_sel_hi:[1,0]
	v_pk_fma_f32 v[6:7], v[8:9], v[6:7], v[46:47]
	v_pk_fma_f32 v[4:5], v[10:11], v[4:5], v[44:45]
	v_pk_mul_f32 v[0:1], v[0:1], v[96:97] op_sel_hi:[1,0]
	v_cvt_pk_bf16_f32 v4, v4, v5
	v_cvt_pk_bf16_f32 v5, v6, v7
	v_pk_mul_f32 v[2:3], v[2:3], v[96:97] op_sel_hi:[1,0]
	s_waitcnt vmcnt(4)
	v_pk_mul_f32 v[0:1], v[36:37], v[0:1]
	s_waitcnt vmcnt(3)
	v_pk_add_f32 v[6:7], v[40:41], 1.0 op_sel_hi:[1,0]
	global_store_dwordx2 v[82:83], v[4:5], off offset:1024
	v_pk_mul_f32 v[2:3], v[38:39], v[2:3]
	v_pk_add_f32 v[4:5], v[42:43], 1.0 op_sel_hi:[1,0]
	s_waitcnt vmcnt(3)
	v_pk_fma_f32 v[0:1], v[6:7], v[0:1], v[32:33]
	v_pk_fma_f32 v[2:3], v[4:5], v[2:3], v[34:35]
	v_cvt_pk_bf16_f32 v0, v0, v1
	v_mov_b64_e32 v[12:13], v[16:17]
	v_cvt_pk_bf16_f32 v1, v2, v3
	global_store_dwordx2 v[82:83], v[0:1], off offset:1536
	v_mov_b64_e32 v[8:9], v[20:21]
	v_mov_b64_e32 v[4:5], v[24:25]
	v_mov_b64_e32 v[0:1], v[28:29]
	v_lshl_add_u64 v[82:83], v[82:83], 0, s[0:1]
	v_mov_b32_e32 v96, v81
	v_mov_b64_e32 v[14:15], v[18:19]
	v_mov_b64_e32 v[10:11], v[22:23]
	v_mov_b64_e32 v[6:7], v[26:27]
	v_mov_b64_e32 v[2:3], v[30:31]
	s_andn2_b64 exec, exec, s[8:9]
	s_cbranch_execz .LBB0_1142
